# tail rows of the three K>1024 projections as a barrier-free pre-step on all workgroups (4 split-K pieces, all loads in flight); GEMM loops run 256 units only; LN tails sum 4 pieces
# speedup vs baseline: 1.0050x; 1.0041x over previous
.LBB0_184:
	s_cmpk_lt_i32 s2, 0x400
	s_cselect_b64 s[0:1], -1, 0
	s_and_b32 s4, s2, 0xffffff00
	v_writelane_b32 v254, s0, 6
	s_cmpk_lt_i32 s2, 0x300
	s_mov_b32 s87, 1
	v_writelane_b32 v254, s1, 7
	s_cselect_b64 s[0:1], -1, 0
	v_cndmask_b32_e64 v193, 0, 1, s[0:1]
	s_and_b64 s[0:1], s[0:1], exec
	s_cselect_b32 s5, 0, 0xfffffd00
	s_cmpk_lg_i32 s4, 0x200
	s_cselect_b64 s[0:1], -1, 0
	v_cndmask_b32_e64 v1, 0, 1, s[0:1]
	v_writelane_b32 v254, s0, 8
	s_movk_i32 s51, 0x60
	v_mov_b32_e32 v173, 0
	v_writelane_b32 v254, s1, 9
	s_and_b64 s[0:1], s[0:1], exec
	s_cselect_b32 s0, s5, 0xfffffe00
	s_cselect_b32 s4, 0x200, 32
	s_cselect_b32 s5, 6, 2
	s_add_i32 s6, s0, s2
	s_cmpk_gt_i32 s2, 0x1ff
	s_cselect_b64 s[0:1], -1, 0
	v_writelane_b32 v254, s0, 10
	v_mov_b32_e32 v194, 0x3eaaaaab
	v_mov_b32_e32 v195, 0x3d2aaaab
	v_writelane_b32 v254, s1, 11
	s_and_b64 s[0:1], s[0:1], exec
	v_readfirstlane_b32 s1, v1
	s_cselect_b32 s1, s1, 2
	s_cselect_b32 s0, s4, 64
	s_cselect_b32 s8, s5, 3
	v_writelane_b32 v254, s1, 12
	s_ashr_i32 s1, s6, 31
	s_lshr_b32 s1, s1, 29
	s_add_i32 s1, s6, s1
	s_ashr_i32 s4, s1, 3
	s_and_b32 s1, s1, -8
	s_sub_i32 s5, s6, s1
	s_cmpk_gt_i32 s2, 0x2ff
	s_cselect_b64 s[6:7], -1, 0
	v_writelane_b32 v254, s6, 13
	v_lshrrev_b32_e32 v1, 20, v0
	v_lshrrev_b32_e32 v0, 10, v0
	v_writelane_b32 v254, s7, 14
	s_and_b64 s[6:7], s[6:7], exec
	s_cselect_b32 s1, 4, 64
	s_cselect_b32 s6, -1, 3
	s_lshl_b32 s7, s1, s8
	s_lshr_b32 s7, s7, 3
	s_or_b32 s10, s7, 1
	s_not_b32 s7, s2
	s_add_i32 s7, s42, s7
	s_add_i32 s6, s6, s8
	v_writelane_b32 v254, s7, 15
	s_and_b32 s7, s2, 7
	s_min_u32 s8, s42, 8
	v_writelane_b32 v254, s8, 16
	s_xor_b32 s8, s7, 7
	s_add_i32 s8, s42, s8
	s_lshl_b32 s6, s5, s6
	s_lshr_b32 s8, s8, 3
	s_lshl_b32 s7, s7, 6
	v_writelane_b32 v254, s8, 17
	s_cmpk_lt_i32 s2, 0x200
	v_writelane_b32 v254, s7, 18
	s_cselect_b64 s[8:9], -1, 0
	s_ashr_i32 s7, s2, 31
	s_lshr_b32 s7, s7, 29
	s_add_i32 s7, s2, s7
	s_ashr_i32 s11, s7, 3
	s_and_b32 s7, s7, -8
	s_sub_i32 s12, s2, s7
	s_lshl_b32 s13, s12, 6
	v_writelane_b32 v254, s8, 19
	s_cmpk_lt_i32 s2, 0x110
	s_mul_i32 s10, s10, s5
	v_writelane_b32 v254, s9, 20
	s_cselect_b64 s[8:9], -1, 0
	v_writelane_b32 v254, s8, 21
	s_cmpk_gt_i32 s2, 0xff
	v_or_b32_e32 v0, v0, v1
	v_writelane_b32 v254, s9, 22
	s_cselect_b64 s[8:9], -1, 0
	v_writelane_b32 v254, s8, 23
	s_cmpk_lt_i32 s2, 0x100
	v_mov_b32_e32 v196, 1
	v_writelane_b32 v254, s9, 24
	s_cselect_b64 s[8:9], -1, 0
	v_writelane_b32 v254, s8, 25
	v_mov_b32_e32 v197, 3
	v_mov_b32_e32 v198, 4
	v_writelane_b32 v254, s9, 26
	s_and_b64 s[8:9], s[8:9], exec
	s_cselect_b32 s7, 0, 2
	v_writelane_b32 v254, s7, 27
	s_mov_b32 s7, 0x60000
	s_cselect_b32 s8, 0, 0xffffff00
	s_cselect_b32 s20, s7, 0x100
	s_mov_b32 s7, 0xb0000
	s_cselect_b32 s14, 64, 4
	s_cselect_b32 s9, 0, 0x100
	s_cselect_b32 s15, 5, 1
	s_cselect_b32 s16, 64, 6
	s_cselect_b32 s19, 64, 11
	s_cselect_b32 s7, s7, 0x100
	s_add_i32 s8, s8, s2
	s_ashr_i32 s17, s8, 31
	s_lshr_b32 s17, s17, 29
	s_add_i32 s17, s8, s17
	s_ashr_i32 s21, s17, 3
	s_and_b32 s17, s17, -8
	s_sub_i32 s22, s8, s17
	s_lshr_b32 s8, s14, 1
	s_lshl_b32 s15, s22, s15
	s_or_b32 s23, s8, 1
	s_lshl_b32 s8, s9, 1
	s_cmpk_lt_i32 s2, 0x2b0
	s_cselect_b64 s[24:25], -1, 0
	v_writelane_b32 v254, s24, 28
	s_cmpk_lt_i32 s2, 0x118
	s_mul_i32 s23, s23, s22
	v_writelane_b32 v254, s25, 29
	s_cselect_b64 s[24:25], -1, 0
	v_writelane_b32 v254, s24, 30
	s_lshr_b32 s17, s16, 1
	s_cmp_lt_u32 s2, s42
	v_writelane_b32 v254, s25, 31
	s_cselect_b32 s18, 12, 18
	v_readlane_b32 s26, v254, 2
	v_readlane_b32 s27, v254, 3
	s_add_u32 s26, s26, s18
	s_addc_u32 s27, s27, 0
	s_mul_i32 s24, s12, 0xb5
	v_writelane_b32 v254, s26, 32
	s_cmpk_lt_i32 s2, 0x5ac
	v_mov_b32_e32 v199, 0x41b17218
	v_writelane_b32 v254, s27, 33
	s_cselect_b64 s[26:27], -1, 0
	s_add_i32 s24, s24, 4
	v_writelane_b32 v254, s26, 34
	s_cmpk_lt_i32 s2, 0x12c
	v_mov_b64_e32 v[178:179], 0x100
	v_writelane_b32 v254, s27, 35
	s_cselect_b64 s[26:27], -1, 0
	s_lshl_b32 s25, s19, 2
	v_writelane_b32 v254, s26, 36
	s_lshr_b32 s18, s19, 1
	s_and_b32 s25, s25, 4
	v_writelane_b32 v254, s27, 37
	s_add_i32 s26, s18, 1
	s_sub_i32 s28, s22, s25
	s_mul_i32 s27, s26, s25
	s_mul_i32 s18, s28, s18
	s_add_i32 s27, s18, s27
	s_cmp_lt_i32 s12, 0
	s_movk_i32 s28, 0x61
	s_cselect_b32 s28, s28, 0x60
	s_mul_i32 s18, s12, 0x41
	s_mul_i32 s28, s12, s28
	s_cselect_b32 s13, s18, s13
	s_add_i32 s28, s28, s11
	s_mul_hi_i32 s18, s28, 0x2aaaaaab
	s_lshr_b32 s29, s18, 31
	s_ashr_i32 s18, s18, 4
	s_add_i32 s18, s18, s29
	s_lshl_b32 s30, s18, 3
	s_mul_i32 s29, s18, 0x60
	s_sub_i32 s18, 64, s30
	s_min_i32 s31, s18, 8
	s_lshr_b32 s18, s22, 31
	s_add_i32 s17, s17, s18
	s_mul_i32 s17, s17, s22
	s_add_i32 s17, s17, s21
	s_ashr_i32 s18, s17, 31
	s_lshr_b32 s18, s18, 27
	s_add_i32 s18, s17, s18
	s_sub_i32 s28, s28, s29
	s_ashr_i32 s29, s18, 5
	s_lshl_b32 s29, s29, 3
	s_sub_i32 s16, s16, s29
	s_andn2_b32 s18, s18, 31
	s_min_i32 s33, s16, 8
	s_sub_i32 s34, s17, s18
	s_cmp_lt_i32 s5, 0
	s_cselect_b32 s5, s10, s6
	s_add_i32 s35, s5, s4
	s_add_i32 s4, s13, s11
	s_ashr_i32 s5, s4, 31
	s_lshr_b32 s5, s5, 26
	s_add_i32 s5, s4, s5
	s_ashr_i32 s6, s5, 6
	s_lshl_b32 s16, s6, 3
	s_sub_i32 s6, 64, s16
	s_andn2_b32 s5, s5, 63
	s_min_i32 s17, s6, 8
	s_sub_i32 s18, s4, s5
	s_cmp_lt_i32 s22, 0
	s_cselect_b32 s4, s23, s15
	s_add_i32 s4, s4, s21
	s_ashr_i32 s5, s4, 31
	s_lshr_b32 s5, s5, 27
	s_add_i32 s5, s4, s5
	s_ashr_i32 s6, s5, 5
	s_lshl_b32 s13, s6, 3
	s_sub_i32 s6, s14, s13
	s_andn2_b32 s5, s5, 31
	s_min_i32 s14, s6, 8
	s_sub_i32 s15, s4, s5
	s_cmp_lt_i32 s12, 4
	s_mulk_i32 s12, 0xb6
	s_cselect_b32 s4, s12, s24
	s_add_i32 s4, s4, s11
	s_mul_hi_i32 s5, s4, 0x2e8ba2e9
	s_lshr_b32 s6, s5, 31
	s_ashr_i32 s5, s5, 5
	s_add_i32 s5, s5, s6
	s_lshl_b32 s10, s5, 3
	s_mul_i32 s6, s5, 0xb0
	s_sub_i32 s5, 0x42, s10
	s_min_i32 s11, s5, 8
	s_sub_i32 s12, s4, s6
	s_cmp_lt_i32 s22, s25
	s_mul_i32 s26, s26, s22
	s_cselect_b32 s4, s26, s27
	s_abs_i32 s22, s31
	v_cvt_f32_u32_e32 v2, s22
	s_add_i32 s6, s4, s21
	s_ashr_i32 s4, s6, 31
	s_lshr_b32 s4, s4, 27
	v_rcp_iflag_f32_e32 v2, v2
	s_sub_i32 s23, 0, s22
	s_add_i32 s21, s6, s4
	s_ashr_i32 s4, s21, 5
	v_mul_f32_e32 v2, 0x4f7ffffe, v2
	v_cvt_u32_f32_e32 v2, v2
	s_andn2_b32 s21, s21, 31
	s_sub_i32 s6, s6, s21
	s_abs_i32 s21, s28
	v_readfirstlane_b32 s24, v2
	s_mul_i32 s23, s23, s24
	s_mul_hi_u32 s23, s24, s23
	s_add_i32 s24, s24, s23
	s_mul_hi_u32 s23, s21, s24
	s_lshl_b32 s4, s4, 3
	s_mul_i32 s24, s23, s22
	s_sub_i32 s5, s19, s4
	s_xor_b32 s19, s28, s31
	s_sub_i32 s21, s21, s24
	s_min_i32 s5, s5, 8
	s_ashr_i32 s19, s19, 31
	s_add_i32 s24, s23, 1
	s_sub_i32 s25, s21, s22
	s_cmp_ge_u32 s21, s22
	s_cselect_b32 s23, s24, s23
	s_cselect_b32 s21, s25, s21
	s_add_i32 s24, s23, 1
	s_cmp_ge_u32 s21, s22
	s_cselect_b32 s21, s24, s23
	s_xor_b32 s21, s21, s19
	s_sub_i32 s24, s21, s19
	s_abs_i32 s21, s33
	v_cvt_f32_u32_e32 v2, s21
	s_mul_i32 s19, s24, s31
	s_sub_i32 s19, s28, s19
	s_add_i32 s26, s30, s19
	v_rcp_iflag_f32_e32 v2, v2
	s_mov_b32 s22, s26
	s_ashr_i32 s27, s26, 31
	v_writelane_b32 v254, s22, 38
	v_mul_f32_e32 v2, 0x4f7ffffe, v2
	v_cvt_u32_f32_e32 v2, v2
	v_writelane_b32 v254, s23, 39
	s_lshl_b64 s[22:23], s[26:27], 19
	v_writelane_b32 v254, s22, 40
	s_ashr_i32 s25, s24, 31
	s_xor_b32 s19, s34, s33
	v_writelane_b32 v254, s23, 41
	s_mov_b32 s22, s24
	v_writelane_b32 v254, s22, 42
	s_ashr_i32 s19, s19, 31
	v_bfrev_b32_e32 v200, 0.5
	v_writelane_b32 v254, s23, 43
	s_lshl_b64 s[22:23], s[24:25], 19
	v_writelane_b32 v254, s22, 44
	v_readfirstlane_b32 s24, v2
	v_cvt_f32_u32_e32 v2, s0
	v_writelane_b32 v254, s23, 45
	s_sub_i32 s23, 0, s21
	s_mul_i32 s23, s23, s24
	s_mul_hi_u32 s23, s24, s23
	s_abs_i32 s22, s34
	s_add_i32 s24, s24, s23
	s_mul_hi_u32 s23, s22, s24
	s_mul_i32 s24, s23, s21
	s_sub_i32 s22, s22, s24
	s_add_i32 s24, s23, 1
	s_sub_i32 s25, s22, s21
	s_cmp_ge_u32 s22, s21
	s_cselect_b32 s23, s24, s23
	s_cselect_b32 s22, s25, s22
	s_add_i32 s24, s23, 1
	s_cmp_ge_u32 s22, s21
	s_cselect_b32 s21, s24, s23
	v_rcp_iflag_f32_e32 v2, v2
	s_xor_b32 s21, s21, s19
	s_sub_i32 s19, s21, s19
	v_writelane_b32 v254, s19, 46
	s_mul_i32 s19, s19, s33
	s_sub_i32 s19, s34, s19
	v_mul_f32_e32 v2, 0x4f7ffffe, v2
	s_add_i32 s26, s29, s19
	v_cvt_u32_f32_e32 v2, v2
	s_mul_hi_i32 s21, s20, s26
	s_mul_i32 s20, s20, s26
	s_lshl_b64 s[20:21], s[20:21], 1
	v_writelane_b32 v254, s20, 47
	v_readfirstlane_b32 s22, v2
	s_ashr_i32 s19, s35, 31
	v_writelane_b32 v254, s21, 48
	s_sub_i32 s21, 0, s0
	s_mul_i32 s21, s21, s22
	s_mul_hi_u32 s21, s22, s21
	s_abs_i32 s20, s35
	s_add_i32 s22, s22, s21
	s_mul_hi_u32 s21, s20, s22
	s_mul_i32 s22, s21, s0
	s_sub_i32 s20, s20, s22
	s_add_i32 s22, s21, 1
	s_sub_i32 s23, s20, s0
	s_cmp_ge_u32 s20, s0
	s_cselect_b32 s21, s22, s21
	s_cselect_b32 s20, s23, s20
	s_add_i32 s22, s21, 1
	s_cmp_ge_u32 s20, s0
	s_cselect_b32 s20, s22, s21
	s_xor_b32 s20, s20, s19
	s_sub_i32 s19, s20, s19
	s_lshl_b32 s20, s19, 3
	s_sub_i32 s1, s1, s20
	s_min_i32 s1, s1, 8
	s_abs_i32 s21, s1
	v_cvt_f32_u32_e32 v2, s21
	s_sub_i32 s23, 0, s21
	s_mul_i32 s19, s19, s0
	s_movk_i32 s22, 0x3ff
	v_rcp_iflag_f32_e32 v1, v2
	s_sub_i32 s0, s35, s19
	v_and_or_b32 v0, v0, s22, v192
	s_abs_i32 s22, s0
	v_mul_f32_e32 v1, 0x4f7ffffe, v1
	v_cvt_u32_f32_e32 v1, v1
	s_xor_b32 s19, s0, s1
	s_ashr_i32 s19, s19, 31
	v_mov_b32_e32 v201, 0xffffff10
	v_readfirstlane_b32 s24, v1
	s_mul_i32 s23, s23, s24
	s_mul_hi_u32 s23, s24, s23
	s_add_i32 s24, s24, s23
	s_mul_hi_u32 s23, s22, s24
	s_mul_i32 s24, s23, s21
	s_sub_i32 s22, s22, s24
	s_add_i32 s24, s23, 1
	s_sub_i32 s25, s22, s21
	s_cmp_ge_u32 s22, s21
	s_cselect_b32 s23, s24, s23
	s_cselect_b32 s22, s25, s22
	s_add_i32 s24, s23, 1
	s_cmp_ge_u32 s22, s21
	s_cselect_b32 s21, s24, s23
	s_xor_b32 s21, s21, s19
	s_sub_i32 s22, s21, s19
	s_mul_i32 s1, s22, s1
	s_sub_i32 s0, s0, s1
	s_abs_i32 s1, s17
	v_cvt_f32_u32_e32 v1, s1
	s_add_i32 s20, s0, s20
	s_mov_b32 s0, s20
	s_ashr_i32 s21, s20, 31
	v_rcp_iflag_f32_e32 v1, v1
	v_writelane_b32 v254, s0, 49
	s_lshl_b64 s[20:21], s[20:21], 19
	s_ashr_i32 s23, s22, 31
	v_writelane_b32 v254, s1, 50
	v_writelane_b32 v254, s20, 51
	v_mul_f32_e32 v1, 0x4f7ffffe, v1
	s_mov_b32 s0, s22
	v_writelane_b32 v254, s21, 52
	v_cvt_u32_f32_e32 v1, v1
	v_writelane_b32 v254, s0, 53
	s_lshl_b64 s[20:21], s[22:23], 19
	s_abs_i32 s19, s18
	v_writelane_b32 v254, s1, 54
	v_writelane_b32 v254, s20, 55
	s_xor_b32 s0, s18, s17
	s_ashr_i32 s0, s0, 31
	v_writelane_b32 v254, s21, 56
	s_sub_i32 s20, 0, s1
	v_readfirstlane_b32 s21, v1
	s_mul_i32 s20, s20, s21
	s_mul_hi_u32 s20, s21, s20
	s_add_i32 s21, s21, s20
	s_mul_hi_u32 s20, s19, s21
	s_mul_i32 s21, s20, s1
	s_sub_i32 s19, s19, s21
	s_add_i32 s21, s20, 1
	s_sub_i32 s22, s19, s1
	s_cmp_ge_u32 s19, s1
	s_cselect_b32 s20, s21, s20
	s_cselect_b32 s19, s22, s19
	s_add_i32 s21, s20, 1
	s_cmp_ge_u32 s19, s1
	s_cselect_b32 s1, s21, s20
	s_xor_b32 s1, s1, s0
	s_sub_i32 s20, s1, s0
	s_abs_i32 s1, s14
	v_cvt_f32_u32_e32 v1, s1
	s_mul_i32 s0, s20, s17
	s_sub_i32 s0, s18, s0
	s_add_i32 s16, s16, s0
	v_rcp_iflag_f32_e32 v1, v1
	s_mov_b32 s0, s16
	s_ashr_i32 s17, s16, 31
	v_writelane_b32 v254, s0, 57
	s_lshl_b64 s[16:17], s[16:17], 19
	v_mul_f32_e32 v1, 0x4f7ffffe, v1
	v_writelane_b32 v254, s1, 58
	v_writelane_b32 v254, s16, 59
	s_mov_b32 s0, s20
	v_cvt_u32_f32_e32 v1, v1
	v_writelane_b32 v254, s17, 60
	s_ashr_i32 s21, s20, 31
	v_writelane_b32 v254, s0, 61
	s_lshl_b64 s[16:17], s[20:21], 19
	v_readfirstlane_b32 s18, v1
	v_writelane_b32 v254, s1, 62
	v_writelane_b32 v254, s16, 63
	s_xor_b32 s0, s15, s14
	s_ashr_i32 s0, s0, 31
	v_writelane_b32 v253, s17, 0
	s_sub_i32 s17, 0, s1
	s_mul_i32 s17, s17, s18
	s_mul_hi_u32 s17, s18, s17
	s_abs_i32 s16, s15
	s_add_i32 s18, s18, s17
	s_mul_hi_u32 s17, s16, s18
	s_mul_i32 s18, s17, s1
	s_sub_i32 s16, s16, s18
	s_add_i32 s18, s17, 1
	s_sub_i32 s19, s16, s1
	s_cmp_ge_u32 s16, s1
	s_cselect_b32 s17, s18, s17
	s_cselect_b32 s16, s19, s16
	s_add_i32 s18, s17, 1
	s_cmp_ge_u32 s16, s1
	s_cselect_b32 s1, s18, s17
	s_xor_b32 s1, s1, s0
	s_sub_i32 s16, s1, s0
	s_abs_i32 s1, s11
	v_cvt_f32_u32_e32 v1, s1
	s_mul_i32 s0, s16, s14
	s_sub_i32 s0, s15, s0
	s_add_i32 s18, s13, s0
	v_rcp_iflag_f32_e32 v1, v1
	s_ashr_i32 s19, s18, 31
	s_lshl_b64 s[14:15], s[18:19], 18
	v_writelane_b32 v253, s14, 1
	v_mul_f32_e32 v1, 0x4f7ffffe, v1
	s_mov_b32 s0, s16
	v_writelane_b32 v253, s15, 2
	v_cvt_u32_f32_e32 v1, v1
	s_ashr_i32 s17, s16, 31
	v_writelane_b32 v253, s0, 3
	s_lshl_b64 s[14:15], s[16:17], 19
	s_abs_i32 s13, s12
	v_writelane_b32 v253, s1, 4
	v_writelane_b32 v253, s14, 5
	s_xor_b32 s0, s12, s11
	s_ashr_i32 s0, s0, 31
	v_writelane_b32 v253, s15, 6
	s_sub_i32 s14, 0, s1
	v_readfirstlane_b32 s15, v1
	s_mul_i32 s14, s14, s15
	s_mul_hi_u32 s14, s15, s14
	s_add_i32 s15, s15, s14
	s_mul_hi_u32 s14, s13, s15
	s_mul_i32 s15, s14, s1
	s_sub_i32 s13, s13, s15
	s_add_i32 s15, s14, 1
	s_sub_i32 s16, s13, s1
	s_cmp_ge_u32 s13, s1
	s_cselect_b32 s14, s15, s14
	s_cselect_b32 s13, s16, s13
	s_add_i32 s15, s14, 1
	s_cmp_ge_u32 s13, s1
	s_cselect_b32 s1, s15, s14
	s_xor_b32 s1, s1, s0
	s_sub_i32 s14, s1, s0
	s_abs_i32 s0, s5
	v_cvt_f32_u32_e32 v1, s0
	s_mul_i32 s1, s14, s11
	s_sub_i32 s1, s12, s1
	s_add_i32 s1, s10, s1
	v_rcp_iflag_f32_e32 v1, v1
	v_writelane_b32 v253, s1, 7
	s_mov_b32 s10, s14
	s_ashr_i32 s15, s14, 31
	v_mul_f32_e32 v1, 0x4f7ffffe, v1
	v_cvt_u32_f32_e32 v1, v1
	v_writelane_b32 v253, s10, 8
	s_xor_b32 s1, s6, s5
	s_ashr_i32 s1, s1, 31
	v_writelane_b32 v253, s11, 9
	s_lshl_b64 s[10:11], s[14:15], 19
	v_writelane_b32 v253, s10, 10
	v_readfirstlane_b32 s12, v1
	s_mul_hi_i32 s15, s18, s9
	v_writelane_b32 v253, s11, 11
	s_sub_i32 s11, 0, s0
	s_mul_i32 s11, s11, s12
	s_mul_hi_u32 s11, s12, s11
	s_abs_i32 s10, s6
	s_add_i32 s12, s12, s11
	s_mul_hi_u32 s11, s10, s12
	s_mul_i32 s12, s11, s0
	s_sub_i32 s10, s10, s12
	s_add_i32 s12, s11, 1
	s_sub_i32 s13, s10, s0
	s_cmp_ge_u32 s10, s0
	s_cselect_b32 s11, s12, s11
	s_mul_hi_i32 s12, s26, s8
	v_writelane_b32 v253, s12, 12
	s_mul_i32 s14, s18, s9
	v_writelane_b32 v253, s14, 13
	s_cselect_b32 s10, s13, s10
	s_add_i32 s12, s11, 1
	v_writelane_b32 v253, s15, 14
	s_cmp_ge_u32 s10, s0
	v_writelane_b32 v253, s26, 15
	s_mul_i32 s0, s26, s8
	v_writelane_b32 v253, s0, 16
	s_cselect_b32 s0, s12, s11
	s_mul_hi_i32 s9, s18, s8
	s_xor_b32 s0, s0, s1
	v_writelane_b32 v253, s9, 17
	s_sub_i32 s1, s0, s1
	s_mov_b32 s0, s18
	v_writelane_b32 v253, s0, 18
	v_mov_b32_e32 v202, 0xff800000
	v_mov_b64_e32 v[184:185], 0x100
	v_writelane_b32 v253, s1, 19
	s_mul_i32 s0, s18, s8
	v_writelane_b32 v253, s0, 20
	s_mul_i32 s0, s1, s5
	s_sub_i32 s0, s6, s0
	s_add_i32 s4, s4, s0
	v_writelane_b32 v253, s1, 21
	s_mul_hi_i32 s1, s7, s4
	s_mul_i32 s0, s7, s4
	s_lshl_b64 s[0:1], s[0:1], 1
	v_writelane_b32 v253, s0, 22
	v_mov_b64_e32 v[186:187], 0xff
	s_movk_i32 s81, 0xc0
	v_writelane_b32 v253, s1, 23
	s_mul_hi_i32 s0, s4, s8
	v_writelane_b32 v253, s0, 24
	v_writelane_b32 v253, s4, 25
	s_mul_i32 s0, s4, s8
	v_writelane_b32 v253, s0, 26
	s_lshl_b32 s0, s42, 4
	v_writelane_b32 v253, s0, 27
	s_add_i32 s0, s2, 0xffffc000
	v_writelane_b32 v253, s0, 28
	s_mov_b32 s0, 0
	v_writelane_b32 v253, s0, 29
	v_cmp_eq_u32_e64 s[4:5], 0, v0
	s_movk_i32 s73, 0x4000
	s_movk_i32 s96, 0x7fff
	v_writelane_b32 v253, s4, 30
	s_movk_i32 s82, 0x2000
	s_movk_i32 s83, 0xd0
	v_writelane_b32 v253, s5, 31
	s_mov_b32 s5, 0
	s_mov_b32 s91, 0x38e38e39
	s_movk_i32 s33, 0x6ff
	s_mov_b32 s97, 0xbfb8aa3b
	s_mov_b32 s90, 0x3dcccccd
	s_mov_b32 s86, 0x800000
	s_mov_b32 s76, 0x3f317217
	s_mov_b32 s77, 0x7f800000
	s_mov_b32 s1, 0xbe800000
	s_movk_i32 s58, 0x4080
	s_mov_b32 s59, 0xfe03f81
	s_movk_i32 s52, 0x1020
	s_movk_i32 s53, 0x2040
	s_movk_i32 s50, 0xf0
	s_movk_i32 s49, 0x4900
	s_movk_i32 s84, 0x407f
	s_movk_i32 s79, 0x1600
	s_add_i32 s92, 0, 0x20c00
	s_add_i32 s40, 0, 0x20800
	s_add_i32 s41, 0, 0x20400
	s_mov_b64 s[94:95], 0x80
	s_mov_b32 s20, 0
	s_mov_b32 s48, 0x3e38aa3b
	s_mov_b64 s[74:75], 0x200
	s_mov_b32 s80, 0x3fd744fd
	s_mov_b64 s[46:47], 0x2000
	v_writelane_b32 v253, s4, 32
	s_nop 1
	v_writelane_b32 v253, s5, 33
	s_branch .LBB0_189

.LBB0_576:
	s_andn2_b64 vcc, exec, s[4:5]
	s_cbranch_vccnz .LBB0_635
	v_readlane_b32 s4, v254, 0
	v_readlane_b32 s5, v254, 1
	s_load_dwordx2 s[6:7], s[4:5], 0xc0
	v_mov_b32_e32 v0, v192
	v_readlane_b32 s8, v254, 30
	v_readlane_b32 s9, v254, 31
	v_readfirstlane_b32 s4, v0
	v_mov_b32_e32 v0, v192
	s_andn2_b64 vcc, exec, s[8:9]
	s_cbranch_vccnz .LBB0_610
	s_waitcnt lgkmcnt(0)
	s_mul_i32 s5, s20, 0x300000
	s_add_u32 s100, s6, 0xc01000
	s_addc_u32 s101, s7, 0
	s_add_u32 s100, s100, s5
	s_addc_u32 s101, s101, 0
	s_add_u32 s8, s6, 0x120b5000
	s_addc_u32 s9, s7, 0
	v_and_b32_e32 v4, 15, v192
	v_bfe_u32 v5, v192, 4, 2
	v_lshrrev_b32_e32 v6, 6, v192
	v_lshl_add_u32 v6, v6, 4, v4
	s_lshr_b32 s5, s2, 6
	s_mul_i32 s5, s5, 0x300
	v_lshlrev_b32_e32 v8, 4, v5
	v_add_u32_e32 v8, s5, v8
	v_mul_u32_u24_e32 v7, 0xc00, v6
	v_add_u32_e32 v7, v7, v8
	s_and_b32 s5, s2, 63
	s_lshl_b32 s5, s5, 4
	v_add_u32_e32 v9, s5, v4
	v_mul_u32_u24_e32 v9, 0xc00, v9
	v_add_u32_e32 v9, v9, v8
	global_load_dwordx4 v[12:15], v7, s[8:9]
	global_load_dwordx4 v[16:19], v9, s[100:101]
	global_load_dwordx4 v[20:23], v7, s[8:9] offset:64
	global_load_dwordx4 v[24:27], v9, s[100:101] offset:64
	global_load_dwordx4 v[28:31], v7, s[8:9] offset:128
	global_load_dwordx4 v[32:35], v9, s[100:101] offset:128
	global_load_dwordx4 v[36:39], v7, s[8:9] offset:192
	global_load_dwordx4 v[40:43], v9, s[100:101] offset:192
	global_load_dwordx4 v[44:47], v7, s[8:9] offset:256
	global_load_dwordx4 v[48:51], v9, s[100:101] offset:256
	global_load_dwordx4 v[52:55], v7, s[8:9] offset:320
	global_load_dwordx4 v[56:59], v9, s[100:101] offset:320
	global_load_dwordx4 v[60:63], v7, s[8:9] offset:384
	global_load_dwordx4 v[64:67], v9, s[100:101] offset:384
	global_load_dwordx4 v[68:71], v7, s[8:9] offset:448
	global_load_dwordx4 v[72:75], v9, s[100:101] offset:448
	global_load_dwordx4 v[76:79], v7, s[8:9] offset:512
	global_load_dwordx4 v[80:83], v9, s[100:101] offset:512
	global_load_dwordx4 v[84:87], v7, s[8:9] offset:576
	global_load_dwordx4 v[88:91], v9, s[100:101] offset:576
	global_load_dwordx4 v[92:95], v7, s[8:9] offset:640
	global_load_dwordx4 v[96:99], v9, s[100:101] offset:640
	global_load_dwordx4 v[100:103], v7, s[8:9] offset:704
	global_load_dwordx4 v[104:107], v9, s[100:101] offset:704
	s_lshr_b32 s5, s2, 6
	s_lshl_b32 s5, s5, 19
	v_lshlrev_b32_e32 v10, 11, v6
	v_add_u32_e32 v10, s5, v10
	s_and_b32 s5, s2, 63
	s_lshl_b32 s5, s5, 5
	v_add_u32_e32 v10, s5, v10
	v_lshl_add_u32 v10, v5, 3, v10
	s_waitcnt vmcnt(22)
	v_mfma_f32_16x16x32_bf16 v[0:3], v[16:19], v[12:15], 0
	s_waitcnt vmcnt(20)
	v_mfma_f32_16x16x32_bf16 v[0:3], v[24:27], v[20:23], v[0:3]
	s_waitcnt vmcnt(18)
	v_mfma_f32_16x16x32_bf16 v[0:3], v[32:35], v[28:31], v[0:3]
	s_waitcnt vmcnt(16)
	v_mfma_f32_16x16x32_bf16 v[0:3], v[40:43], v[36:39], v[0:3]
	s_waitcnt vmcnt(14)
	v_mfma_f32_16x16x32_bf16 v[0:3], v[48:51], v[44:47], v[0:3]
	s_waitcnt vmcnt(12)
	v_mfma_f32_16x16x32_bf16 v[0:3], v[56:59], v[52:55], v[0:3]
	s_waitcnt vmcnt(10)
	v_mfma_f32_16x16x32_bf16 v[0:3], v[64:67], v[60:63], v[0:3]
	s_waitcnt vmcnt(8)
	v_mfma_f32_16x16x32_bf16 v[0:3], v[72:75], v[68:71], v[0:3]
	s_waitcnt vmcnt(6)
	v_mfma_f32_16x16x32_bf16 v[0:3], v[80:83], v[76:79], v[0:3]
	s_waitcnt vmcnt(4)
	v_mfma_f32_16x16x32_bf16 v[0:3], v[88:91], v[84:87], v[0:3]
	s_waitcnt vmcnt(2)
	v_mfma_f32_16x16x32_bf16 v[0:3], v[96:99], v[92:95], v[0:3]
	s_waitcnt vmcnt(0)
	v_mfma_f32_16x16x32_bf16 v[0:3], v[104:107], v[100:103], v[0:3]
	s_add_u32 s8, s6, 0x151f9000
	s_addc_u32 s9, s7, 0
	s_nop 7
	s_nop 7
	v_cvt_pk_bf16_f32 v4, v0, v1
	v_cvt_pk_bf16_f32 v5, v2, v3
	global_store_dwordx2 v10, v[4:5], s[8:9] sc1
	v_mov_b32_e32 v0, v192
	v_readlane_b32 s8, v253, 32
	v_readlane_b32 s9, v253, 33
	s_mul_i32 s8, s20, 0x180000
	s_mov_b32 s5, s9
	v_writelane_b32 v253, s4, 32
	s_lshl_b64 s[8:9], s[8:9], 1
	s_mov_b32 s78, s20
	v_writelane_b32 v253, s5, 33
	s_waitcnt lgkmcnt(0)
	s_add_u32 s5, s6, s8
	s_addc_u32 s8, s7, s9
	s_add_u32 s24, s5, 0xc01000
	s_addc_u32 s25, s8, 0
	v_readlane_b32 s8, v254, 46
	s_mul_i32 s5, s8, 0xc0000
	s_add_u32 s20, s24, s5
	s_mul_hi_i32 s5, s8, 0xc0000
	v_readlane_b32 s8, v254, 23
	v_readlane_b32 s9, v254, 24
	s_addc_u32 s21, s25, s5
	s_andn2_b64 vcc, exec, s[8:9]
	s_mov_b32 s62, 24
	s_cbranch_vccnz .LBB0_580
	v_readlane_b32 s5, v253, 16
	s_add_u32 s20, s20, s5
	v_readlane_b32 s5, v253, 12
	s_addc_u32 s21, s21, s5
	s_mov_b32 s62, 4

.LBB0_585:
	s_add_i32 s55, s55, 1
	s_mul_i32 s4, s43, s55
	s_mul_hi_u32 s5, s42, s55
	s_add_i32 s5, s5, s4
	s_mul_i32 s4, s42, s55
	s_add_u32 s22, s4, s2
	s_addc_u32 s23, s5, s3
	v_mov_b64_e32 v[2:3], 0x100
	v_cmp_lt_i64_e64 s[4:5], s[22:23], v[2:3]
	v_mov_b64_e32 v[2:3], 0xff
	v_cmp_gt_i64_e32 vcc, s[22:23], v[2:3]
	s_cbranch_vccnz .LBB0_588
	v_cmp_lt_i64_e32 vcc, s[22:23], v[178:179]
	s_and_b64 s[12:13], vcc, exec
	s_cselect_b32 s12, 0, 0xffffff00
	s_add_i32 s14, s12, s22
	s_and_b64 s[12:13], vcc, exec
	s_cselect_b32 s16, s27, s29
	s_cselect_b32 s17, s26, s28
	s_cselect_b32 s12, 64, 6
	s_ashr_i32 s15, s14, 31
	s_lshr_b32 s15, s15, 29
	s_add_i32 s15, s14, s15
	s_ashr_i32 s22, s15, 3
	s_and_b32 s15, s15, -8
	s_sub_i32 s14, s14, s15
	s_lshr_b32 s13, s12, 1
	s_lshr_b32 s15, s14, 31
	s_add_i32 s13, s13, s15
	s_mul_i32 s13, s14, s13
	s_add_i32 s14, s13, s22
	s_ashr_i32 s13, s14, 31
	s_lshr_b32 s13, s13, 27
	s_add_i32 s15, s14, s13
	s_ashr_i32 s13, s15, 5
	s_lshl_b32 s22, s13, 3
	s_sub_i32 s12, s12, s22
	s_min_i32 s12, s12, 8
	s_abs_i32 s23, s12
	v_cvt_f32_u32_e32 v2, s23
	s_sub_i32 s57, 0, s23
	s_andn2_b32 s15, s15, 31
	s_sub_i32 s14, s14, s15
	v_rcp_iflag_f32_e32 v2, v2
	s_abs_i32 s56, s14
	s_xor_b32 s15, s14, s12
	s_ashr_i32 s15, s15, 31
	v_mul_f32_e32 v2, 0x4f7ffffe, v2
	v_cvt_u32_f32_e32 v2, v2
	s_mov_b32 s13, 0
	v_readfirstlane_b32 s65, v2
	s_mul_i32 s57, s57, s65
	s_mul_hi_u32 s57, s65, s57
	s_add_i32 s65, s65, s57
	s_mul_hi_u32 s57, s56, s65
	s_mul_i32 s65, s57, s23
	s_sub_i32 s56, s56, s65
	s_add_i32 s65, s57, 1
	s_sub_i32 s66, s56, s23
	s_cmp_ge_u32 s56, s23
	s_cselect_b32 s57, s65, s57
	s_cselect_b32 s56, s66, s56
	s_add_i32 s65, s57, 1
	s_cmp_ge_u32 s56, s23
	s_cselect_b32 s23, s65, s57
	s_xor_b32 s23, s23, s15
	s_sub_i32 s56, s23, s15
	s_mul_i32 s12, s56, s12
	s_sub_i32 s12, s14, s12
	s_add_i32 s12, s22, s12
	s_and_b64 vcc, vcc, exec
	s_mov_b32 s14, 0x60000
	s_cselect_b32 s14, s14, 0x100
	s_mul_hi_i32 s15, s14, s12
	s_mul_i32 s14, s14, s12
	s_lshl_b64 s[14:15], s[14:15], 1
	s_add_u32 s14, s17, s14
	s_addc_u32 s15, s16, s15
	s_mul_i32 s16, s56, 0xc0000
	s_mul_hi_i32 s17, s56, 0xc0000
	s_add_u32 s16, s24, s16
	s_addc_u32 s17, s25, s17
	s_mov_b32 s57, 24
	s_cbranch_vccnz .LBB0_588
	s_ashr_i32 s13, s12, 31
	s_lshl_b64 s[22:23], s[12:13], 9
	s_add_u32 s16, s16, s22
	s_addc_u32 s17, s17, s23
	s_mov_b32 s57, 4
	s_mov_b32 s13, 2

.LBB0_858:
	s_andn2_b64 vcc, exec, s[4:5]
	s_cbranch_vccnz .LBB0_923
	v_readlane_b32 s4, v254, 0
	v_readlane_b32 s5, v254, 1
	s_load_dwordx2 s[10:11], s[4:5], 0xc0
	v_mov_b32_e32 v0, v192
	v_readlane_b32 s4, v254, 21
	v_readlane_b32 s5, v254, 22
	v_readfirstlane_b32 s6, v0
	v_mov_b32_e32 v0, v192
	s_andn2_b64 vcc, exec, s[4:5]
	s_cbranch_vccnz .LBB0_898
	s_waitcnt lgkmcnt(0)
	v_readlane_b32 s7, v253, 36
	s_mul_i32 s7, s7, 0x200000
	s_add_u32 s100, s10, 0x1e01000
	s_addc_u32 s101, s11, 0
	s_add_u32 s100, s100, s7
	s_addc_u32 s101, s101, 0
	s_add_u32 s4, s10, 0x110b1000
	s_addc_u32 s5, s11, 0
	v_and_b32_e32 v4, 15, v192
	v_bfe_u32 v5, v192, 4, 2
	v_lshrrev_b32_e32 v6, 6, v192
	v_lshl_add_u32 v6, v6, 4, v4
	s_lshr_b32 s7, s2, 6
	s_mul_i32 s7, s7, 0x200
	v_lshlrev_b32_e32 v8, 4, v5
	v_add_u32_e32 v8, s7, v8
	v_mul_u32_u24_e32 v7, 0x800, v6
	v_add_u32_e32 v7, v7, v8
	s_and_b32 s7, s2, 63
	s_lshl_b32 s7, s7, 4
	v_add_u32_e32 v9, s7, v4
	v_mul_u32_u24_e32 v9, 0x800, v9
	v_add_u32_e32 v9, v9, v8
	global_load_dwordx4 v[12:15], v7, s[4:5]
	global_load_dwordx4 v[16:19], v9, s[100:101]
	global_load_dwordx4 v[20:23], v7, s[4:5] offset:64
	global_load_dwordx4 v[24:27], v9, s[100:101] offset:64
	global_load_dwordx4 v[28:31], v7, s[4:5] offset:128
	global_load_dwordx4 v[32:35], v9, s[100:101] offset:128
	global_load_dwordx4 v[36:39], v7, s[4:5] offset:192
	global_load_dwordx4 v[40:43], v9, s[100:101] offset:192
	global_load_dwordx4 v[44:47], v7, s[4:5] offset:256
	global_load_dwordx4 v[48:51], v9, s[100:101] offset:256
	global_load_dwordx4 v[52:55], v7, s[4:5] offset:320
	global_load_dwordx4 v[56:59], v9, s[100:101] offset:320
	global_load_dwordx4 v[60:63], v7, s[4:5] offset:384
	global_load_dwordx4 v[64:67], v9, s[100:101] offset:384
	global_load_dwordx4 v[68:71], v7, s[4:5] offset:448
	global_load_dwordx4 v[72:75], v9, s[100:101] offset:448
	s_lshr_b32 s7, s2, 6
	s_lshl_b32 s7, s7, 19
	v_lshlrev_b32_e32 v10, 11, v6
	v_add_u32_e32 v10, s7, v10
	s_and_b32 s7, s2, 63
	s_lshl_b32 s7, s7, 5
	v_add_u32_e32 v10, s7, v10
	v_lshl_add_u32 v10, v5, 3, v10
	s_waitcnt vmcnt(14)
	v_mfma_f32_16x16x32_bf16 v[0:3], v[16:19], v[12:15], 0
	s_waitcnt vmcnt(12)
	v_mfma_f32_16x16x32_bf16 v[0:3], v[24:27], v[20:23], v[0:3]
	s_waitcnt vmcnt(10)
	v_mfma_f32_16x16x32_bf16 v[0:3], v[32:35], v[28:31], v[0:3]
	s_waitcnt vmcnt(8)
	v_mfma_f32_16x16x32_bf16 v[0:3], v[40:43], v[36:39], v[0:3]
	s_waitcnt vmcnt(6)
	v_mfma_f32_16x16x32_bf16 v[0:3], v[48:51], v[44:47], v[0:3]
	s_waitcnt vmcnt(4)
	v_mfma_f32_16x16x32_bf16 v[0:3], v[56:59], v[52:55], v[0:3]
	s_waitcnt vmcnt(2)
	v_mfma_f32_16x16x32_bf16 v[0:3], v[64:67], v[60:63], v[0:3]
	s_waitcnt vmcnt(0)
	v_mfma_f32_16x16x32_bf16 v[0:3], v[72:75], v[68:71], v[0:3]
	s_add_u32 s4, s10, 0x151f9000
	s_addc_u32 s5, s11, 0
	s_nop 7
	s_nop 7
	v_cvt_pk_bf16_f32 v4, v0, v1
	v_cvt_pk_bf16_f32 v5, v2, v3
	global_store_dwordx2 v10, v[4:5], s[4:5] sc1
	v_mov_b32_e32 v0, v192
	v_readlane_b32 s4, v254, 25
	v_readlane_b32 s5, v254, 26
	s_andn2_b64 vcc, exec, s[4:5]
	v_readlane_b32 s4, v253, 13
	v_readlane_b32 s5, v253, 14
	s_cbranch_vccnz .LBB0_862
	v_readlane_b32 s4, v253, 1
	v_readlane_b32 s5, v253, 2

.LBB0_869:
	s_add_i32 s61, s61, 1
	s_mul_i32 s4, s43, s61
	s_mul_hi_u32 s5, s42, s61
	s_add_i32 s5, s5, s4
	s_mul_i32 s4, s42, s61
	s_add_u32 s26, s4, s2
	s_addc_u32 s27, s5, s3
	v_mov_b64_e32 v[2:3], 0x100
	v_cmp_lt_i64_e64 s[4:5], s[26:27], v[2:3]
	v_mov_b64_e32 v[2:3], 0xff
	v_cmp_gt_i64_e32 vcc, s[26:27], v[2:3]
	s_cbranch_vccnz .LBB0_876
	v_cmp_lt_i64_e64 s[8:9], s[26:27], v[178:179]
	s_and_b64 s[16:17], s[8:9], exec
	s_cselect_b32 s16, 0, 0xffffff00
	s_add_i32 s20, s16, s26
	s_and_b64 s[16:17], s[8:9], exec
	s_cselect_b32 s18, 64, 4
	s_ashr_i32 s16, s20, 31
	s_lshr_b32 s16, s16, 29
	s_add_i32 s19, s20, s16
	s_and_b32 s16, s19, -8
	v_mov_b64_e32 v[2:3], 0xff
	s_sub_i32 s20, s20, s16
	v_cmp_gt_i64_e64 s[6:7], s[26:27], v[2:3]
	s_cmp_gt_i32 s20, -1
	s_mov_b64 s[16:17], -1
	s_cbranch_scc0 .LBB0_872
	s_and_b64 s[16:17], s[8:9], exec
	s_cselect_b32 s16, 5, 1
	s_lshl_b32 s21, s20, s16
	s_mov_b64 s[16:17], 0

.LBB0_932:
	s_andn2_saveexec_b64 s[4:5], s[4:5]
	s_cbranch_execz .LBB0_937
	v_add_u32_e32 v172, 0xffffc000, v60
	v_lshlrev_b64 v[56:57], 11, v[172:173]
	v_lshl_add_u64 v[56:57], v[22:23], 0, v[56:57]
	s_mov_b64 vcc, 0x80000
	v_lshl_add_u64 v[60:61], v[56:57], 0, vcc
	global_load_dwordx2 v[116:117], v[60:61], off
	global_load_dwordx2 v[118:119], v[60:61], off offset:512
	global_load_dwordx2 v[120:121], v[60:61], off offset:1024
	global_load_dwordx2 v[122:123], v[60:61], off offset:1536
	s_mov_b64 vcc, 0x100000
	v_lshl_add_u64 v[60:61], v[56:57], 0, vcc
	global_load_dwordx2 v[124:125], v[60:61], off
	global_load_dwordx2 v[126:127], v[60:61], off offset:512
	global_load_dwordx2 v[128:129], v[60:61], off offset:1024
	global_load_dwordx2 v[130:131], v[60:61], off offset:1536
	s_mov_b64 vcc, 0x180000
	v_lshl_add_u64 v[60:61], v[56:57], 0, vcc
	global_load_dwordx2 v[132:133], v[60:61], off
	global_load_dwordx2 v[134:135], v[60:61], off offset:512
	global_load_dwordx2 v[136:137], v[60:61], off offset:1024
	global_load_dwordx2 v[138:139], v[60:61], off offset:1536
	s_waitcnt vmcnt(11)
	v_lshlrev_b32_e32 v68, 16, v116
	v_and_b32_e32 v69, 0xffff0000, v116
	v_lshlrev_b32_e32 v70, 16, v117
	v_and_b32_e32 v71, 0xffff0000, v117
	v_pk_add_f32 v[48:49], v[48:49], v[68:69]
	v_pk_add_f32 v[46:47], v[46:47], v[70:71]
	s_waitcnt vmcnt(10)
	v_lshlrev_b32_e32 v68, 16, v118
	v_and_b32_e32 v69, 0xffff0000, v118
	v_lshlrev_b32_e32 v70, 16, v119
	v_and_b32_e32 v71, 0xffff0000, v119
	v_pk_add_f32 v[52:53], v[52:53], v[68:69]
	v_pk_add_f32 v[58:59], v[58:59], v[70:71]
	s_waitcnt vmcnt(9)
	v_lshlrev_b32_e32 v68, 16, v120
	v_and_b32_e32 v69, 0xffff0000, v120
	v_lshlrev_b32_e32 v70, 16, v121
	v_and_b32_e32 v71, 0xffff0000, v121
	v_pk_add_f32 v[42:43], v[42:43], v[68:69]
	v_pk_add_f32 v[54:55], v[54:55], v[70:71]
	s_waitcnt vmcnt(8)
	v_lshlrev_b32_e32 v68, 16, v122
	v_and_b32_e32 v69, 0xffff0000, v122
	v_lshlrev_b32_e32 v70, 16, v123
	v_and_b32_e32 v71, 0xffff0000, v123
	v_pk_add_f32 v[50:51], v[50:51], v[68:69]
	v_pk_add_f32 v[44:45], v[44:45], v[70:71]
	s_waitcnt vmcnt(7)
	v_lshlrev_b32_e32 v68, 16, v124
	v_and_b32_e32 v69, 0xffff0000, v124
	v_lshlrev_b32_e32 v70, 16, v125
	v_and_b32_e32 v71, 0xffff0000, v125
	v_pk_add_f32 v[48:49], v[48:49], v[68:69]
	v_pk_add_f32 v[46:47], v[46:47], v[70:71]
	s_waitcnt vmcnt(6)
	v_lshlrev_b32_e32 v68, 16, v126
	v_and_b32_e32 v69, 0xffff0000, v126
	v_lshlrev_b32_e32 v70, 16, v127
	v_and_b32_e32 v71, 0xffff0000, v127
	v_pk_add_f32 v[52:53], v[52:53], v[68:69]
	v_pk_add_f32 v[58:59], v[58:59], v[70:71]
	s_waitcnt vmcnt(5)
	v_lshlrev_b32_e32 v68, 16, v128
	v_and_b32_e32 v69, 0xffff0000, v128
	v_lshlrev_b32_e32 v70, 16, v129
	v_and_b32_e32 v71, 0xffff0000, v129
	v_pk_add_f32 v[42:43], v[42:43], v[68:69]
	v_pk_add_f32 v[54:55], v[54:55], v[70:71]
	s_waitcnt vmcnt(4)
	v_lshlrev_b32_e32 v68, 16, v130
	v_and_b32_e32 v69, 0xffff0000, v130
	v_lshlrev_b32_e32 v70, 16, v131
	v_and_b32_e32 v71, 0xffff0000, v131
	v_pk_add_f32 v[50:51], v[50:51], v[68:69]
	v_pk_add_f32 v[44:45], v[44:45], v[70:71]
	s_waitcnt vmcnt(3)
	v_lshlrev_b32_e32 v68, 16, v132
	v_and_b32_e32 v69, 0xffff0000, v132
	v_lshlrev_b32_e32 v70, 16, v133
	v_and_b32_e32 v71, 0xffff0000, v133
	v_pk_add_f32 v[48:49], v[48:49], v[68:69]
	v_pk_add_f32 v[46:47], v[46:47], v[70:71]
	s_waitcnt vmcnt(2)
	v_lshlrev_b32_e32 v68, 16, v134
	v_and_b32_e32 v69, 0xffff0000, v134
	v_lshlrev_b32_e32 v70, 16, v135
	v_and_b32_e32 v71, 0xffff0000, v135
	v_pk_add_f32 v[52:53], v[52:53], v[68:69]
	v_pk_add_f32 v[58:59], v[58:59], v[70:71]
	s_waitcnt vmcnt(1)
	v_lshlrev_b32_e32 v68, 16, v136
	v_and_b32_e32 v69, 0xffff0000, v136
	v_lshlrev_b32_e32 v70, 16, v137
	v_and_b32_e32 v71, 0xffff0000, v137
	v_pk_add_f32 v[42:43], v[42:43], v[68:69]
	v_pk_add_f32 v[54:55], v[54:55], v[70:71]
	s_waitcnt vmcnt(0)
	v_lshlrev_b32_e32 v68, 16, v138
	v_and_b32_e32 v69, 0xffff0000, v138
	v_lshlrev_b32_e32 v70, 16, v139
	v_and_b32_e32 v71, 0xffff0000, v139
	v_pk_add_f32 v[50:51], v[50:51], v[68:69]
	v_pk_add_f32 v[44:45], v[44:45], v[70:71]
	v_mov_b32_e32 v62, v52
	v_mov_b32_e32 v63, v53
	v_mov_b32_e32 v60, v58
	v_mov_b32_e32 v61, v59
	v_mov_b32_e32 v66, v42
	v_mov_b32_e32 v67, v43
	v_mov_b32_e32 v64, v54
	v_mov_b32_e32 v65, v55

.LBB0_1040:
	s_andn2_b64 vcc, exec, s[4:5]
	s_cbranch_vccnz .LBB0_1103
	v_readlane_b32 s4, v254, 0
	v_readlane_b32 s5, v254, 1
	s_load_dwordx4 s[8:11], s[4:5], 0xb8
	v_mov_b32_e32 v0, v192
	v_readlane_b32 s6, v254, 36
	v_readlane_b32 s7, v254, 37
	v_readfirstlane_b32 s4, v0
	v_mov_b32_e32 v0, v192
	s_andn2_b64 vcc, exec, s[6:7]
	s_cbranch_vccnz .LBB0_1078
	s_waitcnt lgkmcnt(0)
	s_mul_i32 s5, s20, 0x580000
	s_add_u32 s100, s8, 0x2088000
	s_addc_u32 s101, s9, 0
	s_add_u32 s100, s100, s5
	s_addc_u32 s101, s101, 0
	s_add_u32 s6, s10, 0xe727000
	s_addc_u32 s7, s11, 0
	v_and_b32_e32 v4, 15, v192
	v_bfe_u32 v5, v192, 4, 2
	v_lshrrev_b32_e32 v6, 6, v192
	v_lshl_add_u32 v6, v6, 4, v4
	s_lshr_b32 s5, s2, 6
	s_mul_i32 s5, s5, 0x580
	v_lshlrev_b32_e32 v8, 4, v5
	v_add_u32_e32 v8, s5, v8
	v_mul_u32_u24_e32 v7, 0x1600, v6
	v_add_u32_e32 v7, v7, v8
	s_and_b32 s5, s2, 63
	s_lshl_b32 s5, s5, 4
	v_add_u32_e32 v9, s5, v4
	v_mul_u32_u24_e32 v9, 0x1600, v9
	v_add_u32_e32 v9, v9, v8
	global_load_dwordx4 v[12:15], v7, s[6:7]
	global_load_dwordx4 v[16:19], v9, s[100:101]
	global_load_dwordx4 v[20:23], v7, s[6:7] offset:64
	global_load_dwordx4 v[24:27], v9, s[100:101] offset:64
	global_load_dwordx4 v[28:31], v7, s[6:7] offset:128
	global_load_dwordx4 v[32:35], v9, s[100:101] offset:128
	global_load_dwordx4 v[36:39], v7, s[6:7] offset:192
	global_load_dwordx4 v[40:43], v9, s[100:101] offset:192
	global_load_dwordx4 v[44:47], v7, s[6:7] offset:256
	global_load_dwordx4 v[48:51], v9, s[100:101] offset:256
	global_load_dwordx4 v[52:55], v7, s[6:7] offset:320
	global_load_dwordx4 v[56:59], v9, s[100:101] offset:320
	global_load_dwordx4 v[60:63], v7, s[6:7] offset:384
	global_load_dwordx4 v[64:67], v9, s[100:101] offset:384
	global_load_dwordx4 v[68:71], v7, s[6:7] offset:448
	global_load_dwordx4 v[72:75], v9, s[100:101] offset:448
	global_load_dwordx4 v[76:79], v7, s[6:7] offset:512
	global_load_dwordx4 v[80:83], v9, s[100:101] offset:512
	global_load_dwordx4 v[84:87], v7, s[6:7] offset:576
	global_load_dwordx4 v[88:91], v9, s[100:101] offset:576
	global_load_dwordx4 v[92:95], v7, s[6:7] offset:640
	global_load_dwordx4 v[96:99], v9, s[100:101] offset:640
	global_load_dwordx4 v[100:103], v7, s[6:7] offset:704
	global_load_dwordx4 v[104:107], v9, s[100:101] offset:704
	global_load_dwordx4 v[108:111], v7, s[6:7] offset:768
	global_load_dwordx4 v[112:115], v9, s[100:101] offset:768
	global_load_dwordx4 v[116:119], v7, s[6:7] offset:832
	global_load_dwordx4 v[120:123], v9, s[100:101] offset:832
	global_load_dwordx4 v[124:127], v7, s[6:7] offset:896
	global_load_dwordx4 v[128:131], v9, s[100:101] offset:896
	global_load_dwordx4 v[132:135], v7, s[6:7] offset:960
	global_load_dwordx4 v[136:139], v9, s[100:101] offset:960
	global_load_dwordx4 v[140:143], v7, s[6:7] offset:1024
	global_load_dwordx4 v[144:147], v9, s[100:101] offset:1024
	global_load_dwordx4 v[148:151], v7, s[6:7] offset:1088
	global_load_dwordx4 v[152:155], v9, s[100:101] offset:1088
	global_load_dwordx4 v[156:159], v7, s[6:7] offset:1152
	global_load_dwordx4 v[160:163], v9, s[100:101] offset:1152
	global_load_dwordx4 v[164:167], v7, s[6:7] offset:1216
	global_load_dwordx4 v[168:171], v9, s[100:101] offset:1216
	global_load_dwordx4 v[204:207], v7, s[6:7] offset:1280
	global_load_dwordx4 v[208:211], v9, s[100:101] offset:1280
	global_load_dwordx4 v[212:215], v7, s[6:7] offset:1344
	global_load_dwordx4 v[216:219], v9, s[100:101] offset:1344
	s_lshr_b32 s5, s2, 6
	s_lshl_b32 s5, s5, 19
	v_lshlrev_b32_e32 v10, 11, v6
	v_add_u32_e32 v10, s5, v10
	s_and_b32 s5, s2, 63
	s_lshl_b32 s5, s5, 5
	v_add_u32_e32 v10, s5, v10
	v_lshl_add_u32 v10, v5, 3, v10
	s_waitcnt vmcnt(42)
	v_mfma_f32_16x16x32_bf16 v[0:3], v[16:19], v[12:15], 0
	s_waitcnt vmcnt(40)
	v_mfma_f32_16x16x32_bf16 v[0:3], v[24:27], v[20:23], v[0:3]
	s_waitcnt vmcnt(38)
	v_mfma_f32_16x16x32_bf16 v[0:3], v[32:35], v[28:31], v[0:3]
	s_waitcnt vmcnt(36)
	v_mfma_f32_16x16x32_bf16 v[0:3], v[40:43], v[36:39], v[0:3]
	s_waitcnt vmcnt(34)
	v_mfma_f32_16x16x32_bf16 v[0:3], v[48:51], v[44:47], v[0:3]
	s_waitcnt vmcnt(32)
	v_mfma_f32_16x16x32_bf16 v[0:3], v[56:59], v[52:55], v[0:3]
	s_waitcnt vmcnt(30)
	v_mfma_f32_16x16x32_bf16 v[0:3], v[64:67], v[60:63], v[0:3]
	s_waitcnt vmcnt(28)
	v_mfma_f32_16x16x32_bf16 v[0:3], v[72:75], v[68:71], v[0:3]
	s_waitcnt vmcnt(26)
	v_mfma_f32_16x16x32_bf16 v[0:3], v[80:83], v[76:79], v[0:3]
	s_waitcnt vmcnt(24)
	v_mfma_f32_16x16x32_bf16 v[0:3], v[88:91], v[84:87], v[0:3]
	s_waitcnt vmcnt(22)
	v_mfma_f32_16x16x32_bf16 v[0:3], v[96:99], v[92:95], v[0:3]
	s_waitcnt vmcnt(20)
	v_mfma_f32_16x16x32_bf16 v[0:3], v[104:107], v[100:103], v[0:3]
	s_waitcnt vmcnt(18)
	v_mfma_f32_16x16x32_bf16 v[0:3], v[112:115], v[108:111], v[0:3]
	s_waitcnt vmcnt(16)
	v_mfma_f32_16x16x32_bf16 v[0:3], v[120:123], v[116:119], v[0:3]
	s_waitcnt vmcnt(14)
	v_mfma_f32_16x16x32_bf16 v[0:3], v[128:131], v[124:127], v[0:3]
	s_waitcnt vmcnt(12)
	v_mfma_f32_16x16x32_bf16 v[0:3], v[136:139], v[132:135], v[0:3]
	s_waitcnt vmcnt(10)
	v_mfma_f32_16x16x32_bf16 v[0:3], v[144:147], v[140:143], v[0:3]
	s_waitcnt vmcnt(8)
	v_mfma_f32_16x16x32_bf16 v[0:3], v[152:155], v[148:151], v[0:3]
	s_waitcnt vmcnt(6)
	v_mfma_f32_16x16x32_bf16 v[0:3], v[160:163], v[156:159], v[0:3]
	s_waitcnt vmcnt(4)
	v_mfma_f32_16x16x32_bf16 v[0:3], v[168:171], v[164:167], v[0:3]
	s_waitcnt vmcnt(2)
	v_mfma_f32_16x16x32_bf16 v[0:3], v[208:211], v[204:207], v[0:3]
	s_waitcnt vmcnt(0)
	v_mfma_f32_16x16x32_bf16 v[0:3], v[216:219], v[212:215], v[0:3]
	s_add_u32 s6, s10, 0x151f9000
	s_addc_u32 s7, s11, 0
	s_nop 7
	s_nop 7
	v_cvt_pk_bf16_f32 v4, v0, v1
	v_cvt_pk_bf16_f32 v5, v2, v3
	global_store_dwordx2 v10, v[4:5], s[6:7] sc1
	v_mov_b32_e32 v0, v192
	v_readlane_b32 s6, v253, 32
	v_readlane_b32 s7, v253, 33
	s_mul_i32 s6, s20, 0x2c0000
	s_mov_b32 s5, s7
	v_writelane_b32 v253, s4, 32
	s_lshl_b64 s[6:7], s[6:7], 1
	s_mov_b32 s65, 44
	v_writelane_b32 v253, s5, 33
	s_waitcnt lgkmcnt(0)
	s_add_u32 s5, s8, s6
	s_addc_u32 s6, s9, s7
	s_add_u32 s26, s5, 0x2088000
	s_addc_u32 s27, s6, 0
	v_readlane_b32 s6, v253, 21
	s_mul_i32 s5, s6, 0x160000
	s_add_u32 s20, s26, s5
	s_mul_hi_i32 s5, s6, 0x160000
	v_readlane_b32 s6, v254, 23
	v_readlane_b32 s7, v254, 24
	s_addc_u32 s21, s27, s5
	s_andn2_b64 vcc, exec, s[6:7]
	s_cbranch_vccnz .LBB0_1044
	v_readlane_b32 s5, v253, 26
	s_add_u32 s20, s20, s5
	v_readlane_b32 s5, v253, 24
	s_addc_u32 s21, s21, s5
	s_mov_b32 s65, 4

.LBB0_1112:
	s_waitcnt vmcnt(8)
	v_lshlrev_b32_e32 v2, 16, v8
	v_and_b32_e32 v3, 0xffff0000, v8
	s_waitcnt vmcnt(4)
	v_lshlrev_b32_e32 v62, 16, v18
	v_and_b32_e32 v63, 0xffff0000, v18
	v_lshlrev_b32_e32 v60, 16, v9
	v_and_b32_e32 v61, 0xffff0000, v9
	v_lshlrev_b32_e32 v64, 16, v19
	v_and_b32_e32 v65, 0xffff0000, v19
	v_pk_add_f32 v[2:3], v[2:3], v[62:63]
	v_lshlrev_b32_e32 v62, 16, v4
	v_and_b32_e32 v63, 0xffff0000, v4
	v_pk_add_f32 v[60:61], v[60:61], v[64:65]
	v_lshlrev_b32_e32 v64, 16, v5
	v_and_b32_e32 v65, 0xffff0000, v5
	v_pk_add_f32 v[62:63], v[62:63], 0 op_sel_hi:[1,0]
	v_pk_add_f32 v[64:65], v[64:65], 0 op_sel_hi:[1,0]
	v_pk_fma_f32 v[2:3], v[2:3], s[80:81], v[62:63] op_sel_hi:[1,0,1]
	v_pk_fma_f32 v[74:75], v[60:61], s[80:81], v[64:65] op_sel_hi:[1,0,1]
	v_pk_mul_f32 v[64:65], v[2:3], v[2:3]
	v_pk_mul_f32 v[62:63], v[74:75], v[74:75]
	v_fmac_f32_e32 v65, v2, v2
	v_add_f32_e32 v76, v62, v65
	v_lshlrev_b32_e32 v62, 16, v10
	v_and_b32_e32 v63, 0xffff0000, v10
	s_waitcnt vmcnt(3)
	v_lshlrev_b32_e32 v66, 16, v20
	v_and_b32_e32 v67, 0xffff0000, v20
	v_pk_add_f32 v[62:63], v[62:63], v[66:67]
	v_lshlrev_b32_e32 v66, 16, v6
	v_and_b32_e32 v67, 0xffff0000, v6
	v_lshlrev_b32_e32 v64, 16, v11
	v_and_b32_e32 v65, 0xffff0000, v11
	v_lshlrev_b32_e32 v68, 16, v21
	v_and_b32_e32 v69, 0xffff0000, v21
	v_pk_add_f32 v[66:67], v[66:67], 0 op_sel_hi:[1,0]
	v_add_f32_e32 v1, v2, v3
	v_pk_add_f32 v[64:65], v[64:65], v[68:69]
	v_lshlrev_b32_e32 v68, 16, v7
	v_and_b32_e32 v69, 0xffff0000, v7
	v_pk_fma_f32 v[70:71], v[62:63], s[80:81], v[66:67] op_sel_hi:[1,0,1]
	v_add_f32_e32 v61, v74, v1
	v_pk_add_f32 v[68:69], v[68:69], 0 op_sel_hi:[1,0]
	v_mul_f32_e32 v60, v71, v71
	v_pk_fma_f32 v[72:73], v[64:65], s[80:81], v[68:69] op_sel_hi:[1,0,1]
	v_pk_fma_f32 v[62:63], v[70:71], v[70:71], v[60:61] op_sel_hi:[1,1,0]
	v_mul_f32_e32 v60, v73, v73
	v_pk_fma_f32 v[62:63], v[72:73], v[72:73], v[62:63]
	s_waitcnt vmcnt(2)
	v_lshlrev_b32_e32 v66, 16, v22
	v_pk_add_f32 v[82:83], v[60:61], v[62:63] op_sel_hi:[0,1]
	v_lshlrev_b32_e32 v62, 16, v12
	v_and_b32_e32 v63, 0xffff0000, v12
	v_and_b32_e32 v67, 0xffff0000, v22
	v_pk_add_f32 v[62:63], v[62:63], v[66:67]
	v_lshlrev_b32_e32 v66, 16, v16
	v_and_b32_e32 v67, 0xffff0000, v16
	v_lshlrev_b32_e32 v64, 16, v13
	v_and_b32_e32 v65, 0xffff0000, v13
	v_lshlrev_b32_e32 v68, 16, v23
	v_and_b32_e32 v69, 0xffff0000, v23
	v_pk_add_f32 v[66:67], v[66:67], 0 op_sel_hi:[1,0]
	v_pk_add_f32 v[64:65], v[64:65], v[68:69]
	v_lshlrev_b32_e32 v68, 16, v17
	v_and_b32_e32 v69, 0xffff0000, v17
	v_pk_fma_f32 v[66:67], v[62:63], s[80:81], v[66:67] op_sel_hi:[1,0,1]
	v_pk_add_f32 v[68:69], v[68:69], 0 op_sel_hi:[1,0]
	v_mul_f32_e32 v60, v67, v67
	v_pk_fma_f32 v[68:69], v[64:65], s[80:81], v[68:69] op_sel_hi:[1,0,1]
	v_pk_fma_f32 v[62:63], v[66:67], v[66:67], v[60:61] op_sel_hi:[1,1,0]
	v_mul_f32_e32 v60, v69, v69
	v_pk_fma_f32 v[62:63], v[68:69], v[68:69], v[62:63]
	s_waitcnt vmcnt(1)
	v_lshlrev_b32_e32 v94, 16, v24
	v_pk_add_f32 v[92:93], v[60:61], v[62:63] op_sel_hi:[0,1]
	v_lshlrev_b32_e32 v62, 16, v14
	v_and_b32_e32 v63, 0xffff0000, v14
	v_and_b32_e32 v95, 0xffff0000, v24
	v_lshlrev_b32_e32 v64, 16, v15
	v_and_b32_e32 v65, 0xffff0000, v15
	v_lshlrev_b32_e32 v96, 16, v25
	v_and_b32_e32 v97, 0xffff0000, v25
	v_pk_add_f32 v[62:63], v[62:63], v[94:95]
	s_waitcnt vmcnt(0)
	v_lshlrev_b32_e32 v94, 16, v26
	v_and_b32_e32 v95, 0xffff0000, v26
	v_add_f32_e32 v1, v70, v71
	v_pk_add_f32 v[64:65], v[64:65], v[96:97]
	v_lshlrev_b32_e32 v96, 16, v27
	v_and_b32_e32 v97, 0xffff0000, v27
	v_pk_add_f32 v[94:95], v[94:95], 0 op_sel_hi:[1,0]
	v_add_f32_e32 v1, v72, v1
	v_pk_add_f32 v[96:97], v[96:97], 0 op_sel_hi:[1,0]
	v_pk_fma_f32 v[62:63], v[62:63], s[80:81], v[94:95] op_sel_hi:[1,0,1]
	v_mul_f32_e32 v78, v75, v75
	v_add_f32_e32 v81, v73, v1
	v_add_f32_e32 v1, v66, v67
	v_pk_fma_f32 v[64:65], v[64:65], s[80:81], v[96:97] op_sel_hi:[1,0,1]
	v_mul_f32_e32 v94, v62, v62
	v_mul_f32_e32 v60, v63, v63
	v_mov_b32_e32 v79, v62
	v_mov_b32_e32 v77, v63
	v_mov_b32_e32 v95, v75
	v_add_f32_e32 v1, v68, v1
	v_mul_f32_e32 v80, v64, v64
	v_pk_add_f32 v[76:77], v[78:79], v[76:77]
	v_mov_b32_e32 v83, v64
	v_pk_add_f32 v[60:61], v[94:95], v[60:61]
	v_add_f32_e32 v85, v69, v1
	v_mul_f32_e32 v84, v65, v65
	v_pk_add_f32 v[76:77], v[82:83], v[76:77]
	v_mov_b32_e32 v93, v65
	v_pk_add_f32 v[60:61], v[80:81], v[60:61]
	v_pk_add_f32 v[76:77], v[92:93], v[76:77]
	v_pk_add_f32 v[60:61], v[84:85], v[60:61]
	s_movk_i32 s0, 0x3fff
	v_pk_add_f32 v[76:77], v[76:77], v[60:61]
	v_cmp_lt_i32_e32 vcc, s0, v0
	s_and_saveexec_b64 s[6:7], vcc
	s_cbranch_execz .LBB0_1116
	v_mov_b32_e32 v53, v173
	v_lshlrev_b64 v[60:61], 11, v[52:53]
	v_lshl_add_u64 v[60:61], v[50:51], 0, v[60:61]
	s_mov_b64 s[8:9], 0
	s_mov_b64 s[8:9], 0x15279000
	v_lshl_add_u64 v[78:79], v[60:61], 0, s[8:9]
	global_load_dwordx2 v[114:115], v[78:79], off
	global_load_dwordx2 v[116:117], v[78:79], off offset:512
	global_load_dwordx2 v[118:119], v[78:79], off offset:1024
	global_load_dwordx2 v[120:121], v[78:79], off offset:1536
	s_mov_b64 s[8:9], 0x152f9000
	v_lshl_add_u64 v[78:79], v[60:61], 0, s[8:9]
	global_load_dwordx2 v[122:123], v[78:79], off
	global_load_dwordx2 v[124:125], v[78:79], off offset:512
	global_load_dwordx2 v[126:127], v[78:79], off offset:1024
	global_load_dwordx2 v[128:129], v[78:79], off offset:1536
	s_mov_b64 s[8:9], 0x15379000
	v_lshl_add_u64 v[78:79], v[60:61], 0, s[8:9]
	global_load_dwordx2 v[130:131], v[78:79], off
	global_load_dwordx2 v[132:133], v[78:79], off offset:512
	global_load_dwordx2 v[134:135], v[78:79], off offset:1024
	global_load_dwordx2 v[136:137], v[78:79], off offset:1536
	s_waitcnt vmcnt(11)
	v_lshlrev_b32_e32 v80, 16, v114
	v_and_b32_e32 v81, 0xffff0000, v114
	v_lshlrev_b32_e32 v82, 16, v115
	v_and_b32_e32 v83, 0xffff0000, v115
	v_pk_add_f32 v[2:3], v[2:3], v[80:81]
	v_pk_add_f32 v[74:75], v[74:75], v[82:83]
	s_waitcnt vmcnt(10)
	v_lshlrev_b32_e32 v80, 16, v116
	v_and_b32_e32 v81, 0xffff0000, v116
	v_lshlrev_b32_e32 v82, 16, v117
	v_and_b32_e32 v83, 0xffff0000, v117
	v_pk_add_f32 v[70:71], v[70:71], v[80:81]
	v_pk_add_f32 v[72:73], v[72:73], v[82:83]
	s_waitcnt vmcnt(9)
	v_lshlrev_b32_e32 v80, 16, v118
	v_and_b32_e32 v81, 0xffff0000, v118
	v_lshlrev_b32_e32 v82, 16, v119
	v_and_b32_e32 v83, 0xffff0000, v119
	v_pk_add_f32 v[66:67], v[66:67], v[80:81]
	v_pk_add_f32 v[68:69], v[68:69], v[82:83]
	s_waitcnt vmcnt(8)
	v_lshlrev_b32_e32 v80, 16, v120
	v_and_b32_e32 v81, 0xffff0000, v120
	v_lshlrev_b32_e32 v82, 16, v121
	v_and_b32_e32 v83, 0xffff0000, v121
	v_pk_add_f32 v[62:63], v[62:63], v[80:81]
	v_pk_add_f32 v[64:65], v[64:65], v[82:83]
	s_waitcnt vmcnt(7)
	v_lshlrev_b32_e32 v80, 16, v122
	v_and_b32_e32 v81, 0xffff0000, v122
	v_lshlrev_b32_e32 v82, 16, v123
	v_and_b32_e32 v83, 0xffff0000, v123
	v_pk_add_f32 v[2:3], v[2:3], v[80:81]
	v_pk_add_f32 v[74:75], v[74:75], v[82:83]
	s_waitcnt vmcnt(6)
	v_lshlrev_b32_e32 v80, 16, v124
	v_and_b32_e32 v81, 0xffff0000, v124
	v_lshlrev_b32_e32 v82, 16, v125
	v_and_b32_e32 v83, 0xffff0000, v125
	v_pk_add_f32 v[70:71], v[70:71], v[80:81]
	v_pk_add_f32 v[72:73], v[72:73], v[82:83]
	s_waitcnt vmcnt(5)
	v_lshlrev_b32_e32 v80, 16, v126
	v_and_b32_e32 v81, 0xffff0000, v126
	v_lshlrev_b32_e32 v82, 16, v127
	v_and_b32_e32 v83, 0xffff0000, v127
	v_pk_add_f32 v[66:67], v[66:67], v[80:81]
	v_pk_add_f32 v[68:69], v[68:69], v[82:83]
	s_waitcnt vmcnt(4)
	v_lshlrev_b32_e32 v80, 16, v128
	v_and_b32_e32 v81, 0xffff0000, v128
	v_lshlrev_b32_e32 v82, 16, v129
	v_and_b32_e32 v83, 0xffff0000, v129
	v_pk_add_f32 v[62:63], v[62:63], v[80:81]
	v_pk_add_f32 v[64:65], v[64:65], v[82:83]
	s_waitcnt vmcnt(3)
	v_lshlrev_b32_e32 v80, 16, v130
	v_and_b32_e32 v81, 0xffff0000, v130
	v_lshlrev_b32_e32 v82, 16, v131
	v_and_b32_e32 v83, 0xffff0000, v131
	v_pk_add_f32 v[2:3], v[2:3], v[80:81]
	v_pk_add_f32 v[74:75], v[74:75], v[82:83]
	s_waitcnt vmcnt(2)
	v_lshlrev_b32_e32 v80, 16, v132
	v_and_b32_e32 v81, 0xffff0000, v132
	v_lshlrev_b32_e32 v82, 16, v133
	v_and_b32_e32 v83, 0xffff0000, v133
	v_pk_add_f32 v[70:71], v[70:71], v[80:81]
	v_pk_add_f32 v[72:73], v[72:73], v[82:83]
	s_waitcnt vmcnt(1)
	v_lshlrev_b32_e32 v80, 16, v134
	v_and_b32_e32 v81, 0xffff0000, v134
	v_lshlrev_b32_e32 v82, 16, v135
	v_and_b32_e32 v83, 0xffff0000, v135
	v_pk_add_f32 v[66:67], v[66:67], v[80:81]
	v_pk_add_f32 v[68:69], v[68:69], v[82:83]
	s_waitcnt vmcnt(0)
	v_lshlrev_b32_e32 v80, 16, v136
	v_and_b32_e32 v81, 0xffff0000, v136
	v_lshlrev_b32_e32 v82, 16, v137
	v_and_b32_e32 v83, 0xffff0000, v137
	v_pk_add_f32 v[62:63], v[62:63], v[80:81]
	v_pk_add_f32 v[64:65], v[64:65], v[82:83]
	v_pk_mul_f32 v[78:79], v[2:3], v[2:3]
	v_pk_add_f32 v[80:81], v[2:3], v[2:3] op_sel_hi:[0,1]
	v_mul_f32_e32 v60, v3, v3
	v_mov_b32_e32 v79, v81
	v_mov_b32_e32 v61, v74
	v_pk_mul_f32 v[80:81], v[70:71], v[70:71]
	v_mul_f32_e32 v76, v74, v74
	v_pk_add_f32 v[60:61], v[60:61], v[78:79]
	v_mov_b32_e32 v77, v75
	v_add_f32_e32 v1, v70, v71
	v_pk_mul_f32 v[78:79], v[72:73], v[72:73]
	v_fmac_f32_e32 v81, v70, v70
	v_pk_mul_f32 v[84:85], v[66:67], v[66:67]
	v_pk_add_f32 v[60:61], v[76:77], v[60:61]
	v_mul_f32_e32 v172, v75, v75
	v_add_f32_e32 v77, v72, v1
	v_add_f32_e32 v78, v78, v81
	v_mul_f32_e32 v76, v73, v73
	v_add_f32_e32 v1, v66, v67
	v_pk_mul_f32 v[82:83], v[68:69], v[68:69]
	v_fmac_f32_e32 v85, v66, v66
	v_pk_mul_f32 v[94:95], v[62:63], v[62:63]
	v_mov_b32_e32 v79, v73
	v_add_f32_e32 v81, v68, v1
	v_add_f32_e32 v82, v82, v85
	v_mul_f32_e32 v80, v69, v69
	v_add_f32_e32 v1, v62, v63
	v_pk_mul_f32 v[92:93], v[64:65], v[64:65]
	v_fmac_f32_e32 v95, v62, v62
	v_pk_add_f32 v[60:61], v[60:61], v[172:173]
	v_pk_add_f32 v[76:77], v[78:79], v[76:77]
	v_mov_b32_e32 v83, v69
	v_add_f32_e32 v85, v64, v1
	v_add_f32_e32 v92, v92, v95
	v_mul_f32_e32 v84, v65, v65
	v_pk_add_f32 v[60:61], v[60:61], v[76:77]
	v_pk_add_f32 v[76:77], v[82:83], v[80:81]
	v_mov_b32_e32 v93, v65
	v_pk_add_f32 v[60:61], v[60:61], v[76:77]
	v_pk_add_f32 v[76:77], v[92:93], v[84:85]
	s_nop 0
	v_pk_add_f32 v[76:77], v[60:61], v[76:77]
